# early weight load + LDS staging after scaling + bank-skewed broadcast layout (union of the two previous epilogue variants)
# baseline (speedup 1.0000x reference)
; #define PG8_STAGE(bufoff, gbase, voff) do { _Pragma("unroll") for (int _i = 0; _i < 2; ++_i) \
;         __builtin_amdgcn_global_load_lds((const unsigned*)((const char*)(gbase) + (voff)[_i]), (LAS unsigned*)(lds + (bufoff) + ldsw + _i * 8192), 16, 0, 0); } while (0)
; #define PG8_LDA(dst, b, h) do { _Pragma("unroll") for (int m = 0; m < 4; ++m) _Pragma("unroll") for (int k = 0; k < 2; ++k) dst[m][k] = *(const LAS bf16x8*)(lds + PG8_SA(b, h) + aoff + m * 2048 + k * 1024); } while (0)
; #define PG8_LDB(dst, b, h) do { _Pragma("unroll") for (int n = 0; n < 2; ++n) _Pragma("unroll") for (int k = 0; k < 2; ++k) dst[n][k] = *(const LAS bf16x8*)(lds + PG8_SB(b, h) + boff + n * 2048 + k * 1024); } while (0)
; #define PG8_MMA(ai, bj, At, Bt) do { __builtin_amdgcn_s_setprio(1); _Pragma("unroll") for (int m = 0; m < 4; ++m) _Pragma("unroll") for (int n = 0; n < 2; ++n) _Pragma("unroll") for (int k = 0; k < 2; ++k) \
;         acc[ai][bj][m][n] = __builtin_amdgcn_mfma_f32_16x16x32_bf16(Bt[n][k], At[m][k], acc[ai][bj][m][n], 0, 0, 0); __builtin_amdgcn_s_setprio(0); } while (0)
; #define PG8_WAIT_V(n) asm volatile("s_waitcnt vmcnt(" #n ")" ::: "memory")
; #define PG8_WAIT_L(n) asm volatile("s_waitcnt lgkmcnt(" #n ")" ::: "memory")
; #define PG8_BAR __builtin_amdgcn_s_barrier()
; #define PG8_SCHED __builtin_amdgcn_sched_barrier(0)
; template <class Epi, bool KREV = false>
; __device__ __forceinline__ void gemm_phase(LAS unsigned char* lds, const Gemm g, const StaticOrder& S, const Epi& E, int wave_s) {
;     ...
;             PG8_LDB(B0, 0, 0); PG8_LDB(B1, 0, 1); PG8_SCHED; PG8_LDA(At, 0, 0); PG8_STAGE(PG8_SA(1, 1), a1 + hstep, voffA);
;             PG8_WAIT_V(8); PG8_WAIT_L(0); PG8_BAR; PG8_MMA(0, 0, At, B0); PG8_MMA(0, 1, At, B1); PG8_BAR; PG8_SCHED;
;             PG8_LDA(At, 0, 1); PG8_STAGE(PG8_SB(0, 0), b2, voffB); PG8_STAGE(PG8_SB(0, 1), b2 + bh, voffB); PG8_STAGE(PG8_SA(0, 0), a2, voffA);
;             PG8_WAIT_V(8); PG8_WAIT_L(0); PG8_BAR; PG8_MMA(1, 0, At, B0); PG8_MMA(1, 1, At, B1); PG8_BAR; PG8_SCHED;
;             PG8_LDB(B0, 1, 0); PG8_LDB(B1, 1, 1); PG8_SCHED; PG8_LDA(At, 1, 0); PG8_STAGE(PG8_SA(0, 1), a2 + hstep, voffA);
;             PG8_WAIT_V(8); PG8_WAIT_L(0); PG8_BAR; PG8_MMA(0, 0, At, B0); PG8_MMA(0, 1, At, B1); PG8_BAR; PG8_SCHED;
.Lsb2:
.LBB0_836:
	v_add_u32_e32 v154, 0x10000, v135
	v_add_u32_e32 v170, 0x14000, v135
	ds_read_b128 v[142:145], v154
	ds_read_b128 v[146:149], v154 offset:1024
	ds_read_b128 v[150:153], v154 offset:2048
	ds_read_b128 v[154:157], v154 offset:3072
	ds_read_b128 v[158:161], v170
	ds_read_b128 v[162:165], v170 offset:1024
	ds_read_b128 v[166:169], v170 offset:2048
	ds_read_b128 v[170:173], v170 offset:3072
	ds_read_b128 v[178:181], v194
	ds_read_b128 v[182:185], v194 offset:1024
	ds_read_b128 v[186:189], v194 offset:2048
	ds_read_b128 v[196:199], v194 offset:3072
	ds_read_b128 v[200:203], v194 offset:4096
	ds_read_b128 v[204:207], v194 offset:5120
	ds_read_b128 v[218:221], v194 offset:6144
	ds_read_b128 v[222:225], v194 offset:7168
	s_add_u32 s56, s54, 0xfff80080
	s_addc_u32 s57, s55, -1
	s_add_i32 s84, 0, 0x10000
	s_cmp_eq_u32 s83, 28
	s_cselect_b32 s59, s73, s57
	s_cselect_b32 s58, s74, s56
	s_cselect_b32 s57, s75, s82
	s_cselect_b32 s56, s77, s80
	s_add_i32 s86, 0, 0x14000
	s_add_i32 m0, s19, 0xc000
	s_nop 0
	global_load_lds_dwordx4 v138, s[54:55]
	s_add_i32 m0, s19, 0xe000
	s_nop 0
	global_load_lds_dwordx4 v140, s[54:55]
	s_waitcnt vmcnt(8)
	s_waitcnt lgkmcnt(0)
	s_barrier
	s_setprio 1
	s_waitcnt lgkmcnt(0)
	v_mfma_f32_16x16x32_bf16 v[124:127], v[142:145], v[178:181], v[124:127]
	v_mfma_f32_16x16x32_bf16 v[120:123], v[150:153], v[178:181], v[120:123]
	v_mfma_f32_16x16x32_bf16 v[68:71], v[142:145], v[186:189], v[68:71]
	v_mfma_f32_16x16x32_bf16 v[64:67], v[150:153], v[186:189], v[64:67]
	v_mfma_f32_16x16x32_bf16 v[60:63], v[142:145], v[200:203], v[60:63]
	v_mfma_f32_16x16x32_bf16 v[20:23], v[150:153], v[200:203], v[20:23]
	v_mfma_f32_16x16x32_bf16 v[108:111], v[142:145], v[218:221], v[108:111]
	v_mfma_f32_16x16x32_bf16 v[104:107], v[150:153], v[218:221], v[104:107]
	v_mfma_f32_16x16x32_bf16 v[124:127], v[146:149], v[182:185], v[124:127]
	v_mfma_f32_16x16x32_bf16 v[120:123], v[154:157], v[182:185], v[120:123]
	v_mfma_f32_16x16x32_bf16 v[68:71], v[146:149], v[196:199], v[68:71]
	v_mfma_f32_16x16x32_bf16 v[64:67], v[154:157], v[196:199], v[64:67]
	v_mfma_f32_16x16x32_bf16 v[60:63], v[146:149], v[204:207], v[60:63]
	v_mfma_f32_16x16x32_bf16 v[20:23], v[154:157], v[204:207], v[20:23]
	v_mfma_f32_16x16x32_bf16 v[108:111], v[146:149], v[222:225], v[108:111]
	v_mfma_f32_16x16x32_bf16 v[104:107], v[154:157], v[222:225], v[104:107]
	s_setprio 0
	s_setprio 1
	v_mfma_f32_16x16x32_bf16 v[116:119], v[158:161], v[178:181], v[116:119]
	v_mfma_f32_16x16x32_bf16 v[112:115], v[166:169], v[178:181], v[112:115]
	v_mfma_f32_16x16x32_bf16 v[52:55], v[158:161], v[186:189], v[52:55]
	v_mfma_f32_16x16x32_bf16 v[48:51], v[166:169], v[186:189], v[48:51]
	v_mfma_f32_16x16x32_bf16 v[44:47], v[158:161], v[200:203], v[44:47]
	v_mfma_f32_16x16x32_bf16 v[16:19], v[166:169], v[200:203], v[16:19]
	v_mfma_f32_16x16x32_bf16 v[100:103], v[158:161], v[218:221], v[100:103]
	v_mfma_f32_16x16x32_bf16 v[96:99], v[166:169], v[218:221], v[96:99]
	v_mfma_f32_16x16x32_bf16 v[116:119], v[162:165], v[182:185], v[116:119]
	v_mfma_f32_16x16x32_bf16 v[112:115], v[170:173], v[182:185], v[112:115]
	v_mfma_f32_16x16x32_bf16 v[52:55], v[162:165], v[196:199], v[52:55]
	v_mfma_f32_16x16x32_bf16 v[48:51], v[170:173], v[196:199], v[48:51]
	v_mfma_f32_16x16x32_bf16 v[44:47], v[162:165], v[204:207], v[44:47]
	v_mfma_f32_16x16x32_bf16 v[16:19], v[170:173], v[204:207], v[16:19]
	v_mfma_f32_16x16x32_bf16 v[100:103], v[162:165], v[222:225], v[100:103]
	s_barrier
	v_mfma_f32_16x16x32_bf16 v[96:99], v[170:173], v[222:225], v[96:99]
	s_setprio 0
	s_add_u32 s98, s56, s2
	s_addc_u32 s99, s57, s3
	s_add_u32 s100, s58, s2
	s_addc_u32 s101, s59, s3
	s_add_i32 s84, s84, s66
	s_mov_b32 m0, s84
	ds_read_b128 v[178:181], v194 offset:16384
	ds_read_b128 v[182:185], v194 offset:17408
	ds_read_b128 v[186:189], v194 offset:18432
	ds_read_b128 v[196:199], v194 offset:19456
	ds_read_b128 v[200:203], v194 offset:20480
	ds_read_b128 v[204:207], v194 offset:21504
	ds_read_b128 v[218:221], v194 offset:22528
	ds_read_b128 v[222:225], v194 offset:23552
	global_load_lds_dwordx4 v176, s[56:57]
	s_add_i32 m0, s84, 0x2000
	s_add_u32 s84, s56, 0x1600000
	s_addc_u32 s85, s57, 0
	s_add_i32 s86, s86, s66
	global_load_lds_dwordx4 v132, s[56:57]
	s_mov_b32 m0, s86
	s_nop 0
	global_load_lds_dwordx4 v176, s[84:85]
	s_add_i32 m0, s86, 0x2000
	s_nop 0
	global_load_lds_dwordx4 v132, s[84:85]
	s_mov_b32 m0, s19
	s_nop 0
	global_load_lds_dwordx4 v128, s[58:59]
	s_mov_b32 m0, s21
	s_nop 0
	global_load_lds_dwordx4 v130, s[58:59]
	s_waitcnt vmcnt(8)
	s_waitcnt lgkmcnt(0)
	s_barrier
; #define PG8_STAGE(bufoff, gbase, voff) do { _Pragma("unroll") for (int _i = 0; _i < 2; ++_i) \
;         __builtin_amdgcn_global_load_lds((const unsigned*)((const char*)(gbase) + (voff)[_i]), (LAS unsigned*)(lds + (bufoff) + ldsw + _i * 8192), 16, 0, 0); } while (0)
; #define PG8_LDA(dst, b, h) do { _Pragma("unroll") for (int m = 0; m < 4; ++m) _Pragma("unroll") for (int k = 0; k < 2; ++k) dst[m][k] = *(const LAS bf16x8*)(lds + PG8_SA(b, h) + aoff + m * 2048 + k * 1024); } while (0)
; #define PG8_LDB(dst, b, h) do { _Pragma("unroll") for (int n = 0; n < 2; ++n) _Pragma("unroll") for (int k = 0; k < 2; ++k) dst[n][k] = *(const LAS bf16x8*)(lds + PG8_SB(b, h) + boff + n * 2048 + k * 1024); } while (0)
; #define PG8_MMA(ai, bj, At, Bt) do { __builtin_amdgcn_s_setprio(1); _Pragma("unroll") for (int m = 0; m < 4; ++m) _Pragma("unroll") for (int n = 0; n < 2; ++n) _Pragma("unroll") for (int k = 0; k < 2; ++k) \
;         acc[ai][bj][m][n] = __builtin_amdgcn_mfma_f32_16x16x32_bf16(Bt[n][k], At[m][k], acc[ai][bj][m][n], 0, 0, 0); __builtin_amdgcn_s_setprio(0); } while (0)
; #define PG8_WAIT_V(n) asm volatile("s_waitcnt vmcnt(" #n ")" ::: "memory")
; #define PG8_WAIT_L(n) asm volatile("s_waitcnt lgkmcnt(" #n ")" ::: "memory")
; #define PG8_BAR __builtin_amdgcn_s_barrier()
; #define PG8_SCHED __builtin_amdgcn_sched_barrier(0)
; template <class Epi, bool KREV = false>
; __device__ __forceinline__ void gemm_phase(LAS unsigned char* lds, const Gemm g, const StaticOrder& S, const Epi& E, int wave_s) {
;     ...
;             PG8_WAIT_V(8); PG8_WAIT_L(0); PG8_BAR; PG8_MMA(1, 0, At, B0); PG8_MMA(1, 1, At, B1); PG8_BAR; PG8_SCHED;
;             PG8_LDB(B0, 1, 0); PG8_LDB(B1, 1, 1); PG8_SCHED; PG8_LDA(At, 1, 0); PG8_STAGE(PG8_SA(0, 1), a2 + hstep, voffA);
;             PG8_WAIT_V(8); PG8_WAIT_L(0); PG8_BAR; PG8_MMA(0, 0, At, B0); PG8_MMA(0, 1, At, B1); PG8_BAR; PG8_SCHED;
;             PG8_LDA(At, 1, 1); PG8_STAGE(PG8_SB(1, 0), b3, voffB); PG8_STAGE(PG8_SB(1, 1), b3 + bh, voffB); PG8_STAGE(PG8_SA(1, 0), a3, voffA);
	s_setprio 1
	s_waitcnt lgkmcnt(0)
	v_mfma_f32_16x16x32_bf16 v[92:95], v[142:145], v[178:181], v[92:95]
	v_mfma_f32_16x16x32_bf16 v[88:91], v[150:153], v[178:181], v[88:91]
	v_mfma_f32_16x16x32_bf16 v[36:39], v[142:145], v[186:189], v[36:39]
	v_mfma_f32_16x16x32_bf16 v[12:15], v[150:153], v[186:189], v[12:15]
	v_mfma_f32_16x16x32_bf16 v[32:35], v[142:145], v[200:203], v[32:35]
	v_mfma_f32_16x16x32_bf16 v[4:7], v[150:153], v[200:203], v[4:7]
	v_mfma_f32_16x16x32_bf16 v[76:79], v[142:145], v[218:221], v[76:79]
	v_mfma_f32_16x16x32_bf16 v[56:59], v[150:153], v[218:221], v[56:59]
	v_mfma_f32_16x16x32_bf16 v[92:95], v[146:149], v[182:185], v[92:95]
	v_mfma_f32_16x16x32_bf16 v[88:91], v[154:157], v[182:185], v[88:91]
	v_mfma_f32_16x16x32_bf16 v[36:39], v[146:149], v[196:199], v[36:39]
	v_mfma_f32_16x16x32_bf16 v[12:15], v[154:157], v[196:199], v[12:15]
	v_mfma_f32_16x16x32_bf16 v[32:35], v[146:149], v[204:207], v[32:35]
	v_mfma_f32_16x16x32_bf16 v[4:7], v[154:157], v[204:207], v[4:7]
	v_mfma_f32_16x16x32_bf16 v[76:79], v[146:149], v[222:225], v[76:79]
	v_mfma_f32_16x16x32_bf16 v[56:59], v[154:157], v[222:225], v[56:59]
	s_setprio 0
	s_setprio 1
	v_mfma_f32_16x16x32_bf16 v[84:87], v[158:161], v[178:181], v[84:87]
	v_mfma_f32_16x16x32_bf16 v[80:83], v[166:169], v[178:181], v[80:83]
	v_mfma_f32_16x16x32_bf16 v[28:31], v[158:161], v[186:189], v[28:31]
	v_mfma_f32_16x16x32_bf16 v[8:11], v[166:169], v[186:189], v[8:11]
	v_mfma_f32_16x16x32_bf16 v[24:27], v[158:161], v[200:203], v[24:27]
	v_mfma_f32_16x16x32_bf16 v[0:3], v[166:169], v[200:203], v[0:3]
	v_mfma_f32_16x16x32_bf16 v[72:75], v[158:161], v[218:221], v[72:75]
	v_mfma_f32_16x16x32_bf16 v[40:43], v[166:169], v[218:221], v[40:43]
	v_mfma_f32_16x16x32_bf16 v[84:87], v[162:165], v[182:185], v[84:87]
	v_mfma_f32_16x16x32_bf16 v[80:83], v[170:173], v[182:185], v[80:83]
	v_mfma_f32_16x16x32_bf16 v[28:31], v[162:165], v[196:199], v[28:31]
	v_mfma_f32_16x16x32_bf16 v[8:11], v[170:173], v[196:199], v[8:11]
	v_mfma_f32_16x16x32_bf16 v[24:27], v[162:165], v[204:207], v[24:27]
	v_mfma_f32_16x16x32_bf16 v[0:3], v[170:173], v[204:207], v[0:3]
	v_mfma_f32_16x16x32_bf16 v[72:75], v[162:165], v[222:225], v[72:75]
	s_barrier
	v_mfma_f32_16x16x32_bf16 v[40:43], v[170:173], v[222:225], v[40:43]
	s_setprio 0
	s_add_i32 s84, 0, 0x18000
	s_add_i32 s85, 0, 0x1c000
	v_add_u32_e32 v154, s84, v135
	v_add_u32_e32 v170, s85, v135
	ds_read_b128 v[142:145], v154
	ds_read_b128 v[146:149], v154 offset:1024
	ds_read_b128 v[150:153], v154 offset:2048
	ds_read_b128 v[154:157], v154 offset:3072
	ds_read_b128 v[158:161], v170
	ds_read_b128 v[162:165], v170 offset:1024
	ds_read_b128 v[166:169], v170 offset:2048
	ds_read_b128 v[170:173], v170 offset:3072
	s_add_u32 s58, s58, 0x80000
	s_addc_u32 s59, s59, 0
	s_mov_b32 m0, s67
	ds_read_b128 v[178:181], v194 offset:32768
	ds_read_b128 v[182:185], v194 offset:33792
	ds_read_b128 v[186:189], v194 offset:34816
	ds_read_b128 v[196:199], v194 offset:35840
	ds_read_b128 v[200:203], v194 offset:36864
	ds_read_b128 v[204:207], v194 offset:37888
	ds_read_b128 v[218:221], v194 offset:38912
	ds_read_b128 v[222:225], v194 offset:39936
	global_load_lds_dwordx4 v128, s[58:59]
	s_mov_b32 m0, s68
	s_nop 0
	global_load_lds_dwordx4 v130, s[58:59]
	s_waitcnt vmcnt(8)
	s_waitcnt lgkmcnt(0)
	s_barrier
	s_setprio 1
	s_waitcnt lgkmcnt(0)
	v_mfma_f32_16x16x32_bf16 v[124:127], v[142:145], v[178:181], v[124:127]
	v_mfma_f32_16x16x32_bf16 v[120:123], v[150:153], v[178:181], v[120:123]
	v_mfma_f32_16x16x32_bf16 v[68:71], v[142:145], v[186:189], v[68:71]
	v_mfma_f32_16x16x32_bf16 v[64:67], v[150:153], v[186:189], v[64:67]
	v_mfma_f32_16x16x32_bf16 v[60:63], v[142:145], v[200:203], v[60:63]
	v_mfma_f32_16x16x32_bf16 v[20:23], v[150:153], v[200:203], v[20:23]
	v_mfma_f32_16x16x32_bf16 v[108:111], v[142:145], v[218:221], v[108:111]
	v_mfma_f32_16x16x32_bf16 v[104:107], v[150:153], v[218:221], v[104:107]
	v_mfma_f32_16x16x32_bf16 v[124:127], v[146:149], v[182:185], v[124:127]
	v_mfma_f32_16x16x32_bf16 v[120:123], v[154:157], v[182:185], v[120:123]
	v_mfma_f32_16x16x32_bf16 v[68:71], v[146:149], v[196:199], v[68:71]
	v_mfma_f32_16x16x32_bf16 v[64:67], v[154:157], v[196:199], v[64:67]
	v_mfma_f32_16x16x32_bf16 v[60:63], v[146:149], v[204:207], v[60:63]
	v_mfma_f32_16x16x32_bf16 v[20:23], v[154:157], v[204:207], v[20:23]
	v_mfma_f32_16x16x32_bf16 v[108:111], v[146:149], v[222:225], v[108:111]
	v_mfma_f32_16x16x32_bf16 v[104:107], v[154:157], v[222:225], v[104:107]
	s_setprio 0
	s_setprio 1
	v_mfma_f32_16x16x32_bf16 v[116:119], v[158:161], v[178:181], v[116:119]
	v_mfma_f32_16x16x32_bf16 v[112:115], v[166:169], v[178:181], v[112:115]
	v_mfma_f32_16x16x32_bf16 v[52:55], v[158:161], v[186:189], v[52:55]
	v_mfma_f32_16x16x32_bf16 v[48:51], v[166:169], v[186:189], v[48:51]
	v_mfma_f32_16x16x32_bf16 v[44:47], v[158:161], v[200:203], v[44:47]
	v_mfma_f32_16x16x32_bf16 v[16:19], v[166:169], v[200:203], v[16:19]
	v_mfma_f32_16x16x32_bf16 v[100:103], v[158:161], v[218:221], v[100:103]
	v_mfma_f32_16x16x32_bf16 v[96:99], v[166:169], v[218:221], v[96:99]
	v_mfma_f32_16x16x32_bf16 v[116:119], v[162:165], v[182:185], v[116:119]
	v_mfma_f32_16x16x32_bf16 v[112:115], v[170:173], v[182:185], v[112:115]
	v_mfma_f32_16x16x32_bf16 v[52:55], v[162:165], v[196:199], v[52:55]
	v_mfma_f32_16x16x32_bf16 v[48:51], v[170:173], v[196:199], v[48:51]
	v_mfma_f32_16x16x32_bf16 v[44:47], v[162:165], v[204:207], v[44:47]
	v_mfma_f32_16x16x32_bf16 v[16:19], v[170:173], v[204:207], v[16:19]
	v_mfma_f32_16x16x32_bf16 v[100:103], v[162:165], v[222:225], v[100:103]
	s_barrier
; #define PG8_STAGE(bufoff, gbase, voff) do { _Pragma("unroll") for (int _i = 0; _i < 2; ++_i) \
;         __builtin_amdgcn_global_load_lds((const unsigned*)((const char*)(gbase) + (voff)[_i]), (LAS unsigned*)(lds + (bufoff) + ldsw + _i * 8192), 16, 0, 0); } while (0)
; #define PG8_LDA(dst, b, h) do { _Pragma("unroll") for (int m = 0; m < 4; ++m) _Pragma("unroll") for (int k = 0; k < 2; ++k) dst[m][k] = *(const LAS bf16x8*)(lds + PG8_SA(b, h) + aoff + m * 2048 + k * 1024); } while (0)
; #define PG8_MMA(ai, bj, At, Bt) do { __builtin_amdgcn_s_setprio(1); _Pragma("unroll") for (int m = 0; m < 4; ++m) _Pragma("unroll") for (int n = 0; n < 2; ++n) _Pragma("unroll") for (int k = 0; k < 2; ++k) \
;         acc[ai][bj][m][n] = __builtin_amdgcn_mfma_f32_16x16x32_bf16(Bt[n][k], At[m][k], acc[ai][bj][m][n], 0, 0, 0); __builtin_amdgcn_s_setprio(0); } while (0)
; #define PG8_WAIT_V(n) asm volatile("s_waitcnt vmcnt(" #n ")" ::: "memory")
; #define PG8_WAIT_L(n) asm volatile("s_waitcnt lgkmcnt(" #n ")" ::: "memory")
; #define PG8_BAR __builtin_amdgcn_s_barrier()
; #define PG8_SCHED __builtin_amdgcn_sched_barrier(0)
;     __device__ __forceinline__ void operator()(f32x4 (&acc)[2][2][4][2], const Unit& u, int wr, int wc, int fr, int fq, const LAS float* rtab) const {
;     ...
;             const f32x4 wg0 = *(const f32x4*)(cw + cn), wg1 = *(const f32x4*)(cw + UP_N + cn), wg2 = *(const f32x4*)(cw + 2 * UP_N + cn), bg = *(const f32x4*)(cb + cn);
;             const f32x4 wu0 = *(const f32x4*)(cw + DFF + cn), wu1 = *(const f32x4*)(cw + UP_N + DFF + cn), wu2 = *(const f32x4*)(cw + 2 * UP_N + DFF + cn), bu = *(const f32x4*)(cb + DFF + cn);
; template <class Epi, bool KREV = false>
; __device__ __forceinline__ void gemm_phase(LAS unsigned char* lds, const Gemm g, const StaticOrder& S, const Epi& E, int wave_s) {
;     ...
;             PG8_LDA(At, 1, 1); PG8_STAGE(PG8_SB(1, 0), b3, voffB); PG8_STAGE(PG8_SB(1, 1), b3 + bh, voffB); PG8_STAGE(PG8_SA(1, 0), a3, voffA);
;             PG8_WAIT_V(8); PG8_WAIT_L(0); PG8_BAR; PG8_MMA(1, 0, At, B0); PG8_MMA(1, 1, At, B1); PG8_BAR; PG8_SCHED;
;         }
;         if (wr == 0) PG8_BAR;
	v_mfma_f32_16x16x32_bf16 v[96:99], v[170:173], v[222:225], v[96:99]
	s_setprio 0
	s_add_i32 s58, s84, s66
	s_mov_b32 m0, s58
	ds_read_b128 v[178:181], v194 offset:49152
	ds_read_b128 v[182:185], v194 offset:50176
	ds_read_b128 v[186:189], v194 offset:51200
	ds_read_b128 v[196:199], v194 offset:52224
	ds_read_b128 v[200:203], v194 offset:53248
	ds_read_b128 v[204:207], v194 offset:54272
	ds_read_b128 v[218:221], v194 offset:55296
	ds_read_b128 v[222:225], v194 offset:56320
	global_load_lds_dwordx4 v176, s[98:99]
	s_add_i32 m0, s58, 0x2000
	s_add_u32 s56, s56, 0x1600080
	s_addc_u32 s57, s57, 0
	s_add_i32 s58, s85, s66
	global_load_lds_dwordx4 v132, s[98:99]
	s_mov_b32 m0, s58
	s_nop 0
	global_load_lds_dwordx4 v176, s[56:57]
	s_add_i32 m0, s58, 0x2000
	s_nop 0
	global_load_lds_dwordx4 v132, s[56:57]
	s_mov_b32 m0, s70
	s_nop 0
	global_load_lds_dwordx4 v128, s[100:101]
	s_mov_b32 m0, s71
	s_nop 0
	global_load_lds_dwordx4 v130, s[100:101]
	s_waitcnt vmcnt(8)
	s_waitcnt lgkmcnt(0)
	s_barrier
	s_setprio 1
	s_waitcnt lgkmcnt(0)
	v_mfma_f32_16x16x32_bf16 v[92:95], v[142:145], v[178:181], v[92:95]
	v_mfma_f32_16x16x32_bf16 v[88:91], v[150:153], v[178:181], v[88:91]
	v_mfma_f32_16x16x32_bf16 v[36:39], v[142:145], v[186:189], v[36:39]
	v_mfma_f32_16x16x32_bf16 v[12:15], v[150:153], v[186:189], v[12:15]
	v_mfma_f32_16x16x32_bf16 v[32:35], v[142:145], v[200:203], v[32:35]
	v_mfma_f32_16x16x32_bf16 v[4:7], v[150:153], v[200:203], v[4:7]
	v_mfma_f32_16x16x32_bf16 v[76:79], v[142:145], v[218:221], v[76:79]
	v_mfma_f32_16x16x32_bf16 v[56:59], v[150:153], v[218:221], v[56:59]
	v_mfma_f32_16x16x32_bf16 v[92:95], v[146:149], v[182:185], v[92:95]
	v_mfma_f32_16x16x32_bf16 v[88:91], v[154:157], v[182:185], v[88:91]
	v_mfma_f32_16x16x32_bf16 v[36:39], v[146:149], v[196:199], v[36:39]
	v_mfma_f32_16x16x32_bf16 v[12:15], v[154:157], v[196:199], v[12:15]
	v_mfma_f32_16x16x32_bf16 v[32:35], v[146:149], v[204:207], v[32:35]
	v_mfma_f32_16x16x32_bf16 v[4:7], v[154:157], v[204:207], v[4:7]
	v_mfma_f32_16x16x32_bf16 v[76:79], v[146:149], v[222:225], v[76:79]
	v_mfma_f32_16x16x32_bf16 v[56:59], v[154:157], v[222:225], v[56:59]
	s_setprio 0
	s_setprio 1
	v_mfma_f32_16x16x32_bf16 v[84:87], v[158:161], v[178:181], v[84:87]
	v_mfma_f32_16x16x32_bf16 v[80:83], v[166:169], v[178:181], v[80:83]
	v_mfma_f32_16x16x32_bf16 v[28:31], v[158:161], v[186:189], v[28:31]
	v_mfma_f32_16x16x32_bf16 v[8:11], v[166:169], v[186:189], v[8:11]
	v_mfma_f32_16x16x32_bf16 v[24:27], v[158:161], v[200:203], v[24:27]
	v_mfma_f32_16x16x32_bf16 v[0:3], v[166:169], v[200:203], v[0:3]
	v_mfma_f32_16x16x32_bf16 v[72:75], v[158:161], v[218:221], v[72:75]
	v_mfma_f32_16x16x32_bf16 v[40:43], v[166:169], v[218:221], v[40:43]
	v_mfma_f32_16x16x32_bf16 v[84:87], v[162:165], v[182:185], v[84:87]
	v_mfma_f32_16x16x32_bf16 v[80:83], v[170:173], v[182:185], v[80:83]
	v_mfma_f32_16x16x32_bf16 v[28:31], v[162:165], v[196:199], v[28:31]
	v_mfma_f32_16x16x32_bf16 v[8:11], v[170:173], v[196:199], v[8:11]
	s_add_i32 s83, s83, 2
	s_add_u32 s54, s54, 0x100
	s_addc_u32 s55, s55, 0
	v_mfma_f32_16x16x32_bf16 v[24:27], v[162:165], v[204:207], v[24:27]
	s_add_u32 s80, s80, 0x100
	s_addc_u32 s82, s82, 0
	v_mfma_f32_16x16x32_bf16 v[0:3], v[170:173], v[204:207], v[0:3]
	s_cmp_gt_u32 s83, 29
	v_mfma_f32_16x16x32_bf16 v[72:75], v[162:165], v[222:225], v[72:75]
	s_barrier
	v_mfma_f32_16x16x32_bf16 v[40:43], v[170:173], v[222:225], v[40:43]
	s_setprio 0
	s_cbranch_scc0 .LBB0_836
	v_lshl_add_u32 v252, s1, 10, v192
	v_mad_u32_u24 v252, v134, 12, v252
	ds_read_b128 v[228:231], v252
	ds_read_b128 v[232:235], v252 offset:512
	v_lshl_or_b32 v213, s0, 7, v193
	v_lshlrev_b32_e32 v253, 2, v213
	v_and_b32_e32 v217, 63, v208
	v_lshrrev_b32_e32 v142, 1, v134
	v_and_b32_e32 v143, 1, v134
	v_and_b32_e32 v178, 3, v142
	v_cmp_eq_u32_e64 s[56:57], 3, v178
	v_cmp_lt_u32_e64 s[54:55], 3, v142
	v_mul_u32_u24_e32 v210, 0xb000, v178
	v_mov_b32_e32 v211, 0
	v_cndmask_b32_e64 v210, v210, 0, s[56:57]
	v_lshl_add_u32 v210, v143, 4, v210
	v_lshl_add_u32 v210, v213, 2, v210
	v_add_u32_e32 v179, 0x5800, v210
	v_cndmask_b32_e64 v210, v210, v179, s[54:55]
	v_mov_b32_e32 v218, s34
	v_mov_b32_e32 v219, s35
	v_mov_b32_e32 v252, s36
	v_mov_b32_e32 v253, s37
	v_cndmask_b32_e64 v218, v218, v252, s[56:57]
	v_cndmask_b32_e64 v219, v219, v253, s[56:57]
	v_lshl_add_u64 v[210:211], v[218:219], 0, v[210:211]
	global_load_dwordx4 v[224:227], v[210:211], off
	v_bfe_u32 v212, v217, 4, 2
	v_and_b32_e32 v195, 1, v212
	v_lshlrev_b32_e32 v195, 8, v195
	v_lshrrev_b32_e32 v179, 1, v212
	v_lshl_add_u32 v195, v179, 13, v195
	v_lshl_add_u32 v195, v212, 4, v195
	v_add_u32_e32 v212, s19, v195
	v_lshl_add_u32 v195, v134, 4, v212
	s_and_b64 vcc, exec, s[38:39]
	s_cbranch_vccz .LBB0_839
	s_barrier
